# index scoring v5: wave halves 0-3/4-7 one tick apart (read tick / MFMA tick with 8 resident B quads), 2 barriers per tile
# speedup vs baseline: 1.0027x; 1.0027x over previous
.Lidx_p_nopf:
	s_waitcnt lgkmcnt(0)
	s_barrier
	s_cmp_lt_u32 s22, 4
	s_cbranch_scc1 .Lidx_even
	s_barrier

.Lidx_e_nost:
	ds_read_b128 v[136:139], v206
	ds_read_b128 v[140:143], v16
	ds_read_b128 v[208:211], v17
	ds_read_b128 v[212:215], v18
	ds_read_b128 v[232:235], v19
	ds_read_b128 v[236:239], v20
	ds_read_b128 v[240:243], v21
	ds_read_b128 v[244:247], v22
	s_cmp_gt_i32 s2, s38
	s_cbranch_scc1 .Lidx_e_nopf
	v_add_co_u32_e32 v248, vcc, 0xffffe000, v112
	s_nop 1
	v_addc_co_u32_e32 v249, vcc, -1, v113, vcc
	global_load_dwordx4 v[96:99], v[248:249], off
	global_load_dwordx4 v[100:103], v[112:113], off
.Lidx_e_nopf:
	s_waitcnt lgkmcnt(0)
	s_barrier
	v_mfma_f32_32x32x16_bf16 v[0:15], v[64:67], v[136:139], 0
	v_max_f32_e32 v216, 0, v216
	v_max_f32_e32 v217, 0, v217
	v_fma_f32 v216, v84, v216, 0
	v_max_f32_e32 v218, 0, v218
	v_mfma_f32_32x32x16_bf16 v[0:15], v[40:43], v[140:143], v[0:15]
	v_fmac_f32_e32 v216, v85, v217
	v_max_f32_e32 v219, 0, v219
	v_fmac_f32_e32 v216, v86, v218
	v_max_f32_e32 v220, 0, v220
	v_mfma_f32_32x32x16_bf16 v[0:15], v[44:47], v[208:211], v[0:15]
	v_fmac_f32_e32 v216, v87, v219
	v_max_f32_e32 v221, 0, v221
	v_fmac_f32_e32 v216, v80, v220
	v_max_f32_e32 v222, 0, v222
	v_mfma_f32_32x32x16_bf16 v[0:15], v[48:51], v[212:215], v[0:15]
	v_fmac_f32_e32 v216, v81, v221
	v_max_f32_e32 v223, 0, v223
	v_fmac_f32_e32 v216, v82, v222
	v_max_f32_e32 v224, 0, v224
	v_mfma_f32_32x32x16_bf16 v[0:15], v[52:55], v[232:235], v[0:15]
	v_fmac_f32_e32 v216, v83, v223
	v_max_f32_e32 v225, 0, v225
	v_fmac_f32_e32 v216, v76, v224
	v_max_f32_e32 v226, 0, v226
	v_mfma_f32_32x32x16_bf16 v[0:15], v[56:59], v[236:239], v[0:15]
	v_fmac_f32_e32 v216, v77, v225
	v_max_f32_e32 v227, 0, v227
	v_fmac_f32_e32 v216, v78, v226
	v_max_f32_e32 v228, 0, v228
	v_mfma_f32_32x32x16_bf16 v[0:15], v[60:63], v[240:243], v[0:15]
	v_fmac_f32_e32 v216, v79, v227
	v_max_f32_e32 v229, 0, v229
	v_fmac_f32_e32 v216, v72, v228
	v_max_f32_e32 v230, 0, v230
	v_mfma_f32_32x32x16_bf16 v[0:15], v[68:71], v[244:247], v[0:15]
	v_fmac_f32_e32 v216, v73, v229
	v_max_f32_e32 v231, 0, v231
	v_fmac_f32_e32 v216, v74, v230
	v_fmac_f32_e32 v216, v75, v231
	ds_write_b32 v207, v216
	s_nop 0
	v_mov_b32_e32 v207, v109
	s_barrier
	s_add_i32 s24, s2, -2
	s_cmp_gt_i32 s24, s38
	s_cbranch_scc1 .Lidx_exit_e
	s_cmp_gt_i32 s3, s38
	s_cbranch_scc1 .Lidx_o_nost
	s_cmp_gt_i32 s2, s38
	s_cbranch_scc1 .Lidx_o_w0
	s_waitcnt vmcnt(2)
	s_branch .Lidx_o_w

.Lidx_o_nost:
	ds_read_b128 v[136:139], v206 offset:16384
	ds_read_b128 v[140:143], v16 offset:16384
	ds_read_b128 v[208:211], v17 offset:16384
	ds_read_b128 v[212:215], v18 offset:16384
	ds_read_b128 v[232:235], v19 offset:16384
	ds_read_b128 v[236:239], v20 offset:16384
	ds_read_b128 v[240:243], v21 offset:16384
	ds_read_b128 v[244:247], v22 offset:16384
	s_add_i32 s24, s2, 1
	s_cmp_gt_i32 s24, s38
	s_cbranch_scc1 .Lidx_o_nopf
	v_add_co_u32_e32 v248, vcc, 0x2000, v112
	s_nop 1
	v_addc_co_u32_e32 v249, vcc, 0, v113, vcc
	global_load_dwordx4 v[88:91], v[248:249], off
	v_add_co_u32_e32 v248, vcc, 0x4000, v112
	s_nop 1
	v_addc_co_u32_e32 v249, vcc, 0, v113, vcc
	global_load_dwordx4 v[92:95], v[248:249], off
.Lidx_o_nopf:
	s_waitcnt lgkmcnt(0)
	s_barrier
	v_mfma_f32_32x32x16_bf16 v[216:231], v[64:67], v[136:139], 0
	v_max_f32_e32 v0, 0, v0
	v_max_f32_e32 v1, 0, v1
	v_fma_f32 v0, v84, v0, 0
	v_max_f32_e32 v2, 0, v2
	v_mfma_f32_32x32x16_bf16 v[216:231], v[40:43], v[140:143], v[216:231]
	v_fmac_f32_e32 v0, v85, v1
	v_max_f32_e32 v3, 0, v3
	v_fmac_f32_e32 v0, v86, v2
	v_max_f32_e32 v4, 0, v4
	v_mfma_f32_32x32x16_bf16 v[216:231], v[44:47], v[208:211], v[216:231]
	v_fmac_f32_e32 v0, v87, v3
	v_max_f32_e32 v5, 0, v5
	v_fmac_f32_e32 v0, v80, v4
	v_max_f32_e32 v6, 0, v6
	v_mfma_f32_32x32x16_bf16 v[216:231], v[48:51], v[212:215], v[216:231]
	v_fmac_f32_e32 v0, v81, v5
	v_max_f32_e32 v7, 0, v7
	v_fmac_f32_e32 v0, v82, v6
	v_max_f32_e32 v8, 0, v8
	v_mfma_f32_32x32x16_bf16 v[216:231], v[52:55], v[232:235], v[216:231]
	v_fmac_f32_e32 v0, v83, v7
	v_max_f32_e32 v9, 0, v9
	v_fmac_f32_e32 v0, v76, v8
	v_max_f32_e32 v10, 0, v10
	v_mfma_f32_32x32x16_bf16 v[216:231], v[56:59], v[236:239], v[216:231]
	v_fmac_f32_e32 v0, v77, v9
	v_max_f32_e32 v11, 0, v11
	v_fmac_f32_e32 v0, v78, v10
	v_max_f32_e32 v12, 0, v12
	v_mfma_f32_32x32x16_bf16 v[216:231], v[60:63], v[240:243], v[216:231]
	v_fmac_f32_e32 v0, v79, v11
	v_max_f32_e32 v13, 0, v13
	v_fmac_f32_e32 v0, v72, v12
	v_max_f32_e32 v14, 0, v14
	v_mfma_f32_32x32x16_bf16 v[216:231], v[68:71], v[244:247], v[216:231]
	v_fmac_f32_e32 v0, v73, v13
	v_max_f32_e32 v15, 0, v15
	v_fmac_f32_e32 v0, v74, v14
	v_fmac_f32_e32 v0, v75, v15
	ds_write_b32 v207, v0
	s_nop 0
	v_add_u32_e32 v207, 0x100, v109
	s_barrier
	s_mov_b64 s[24:25], 0x8000
	s_add_i32 s2, s2, 2
	v_lshl_add_u64 v[112:113], v[112:113], 0, s[24:25]
	s_cmp_gt_i32 s3, s38
	v_add_u32_e32 v109, 0x200, v109
	s_cbranch_scc0 .Lidx_even
	s_cmp_gt_u32 s22, 3
	s_cbranch_scc1 .Lidx_x_o
	s_barrier
.Lidx_x_o:
	s_nop 3
	v_max_f32_e32 v216, 0, v216
	v_max_f32_e32 v217, 0, v217
	v_fma_f32 v216, v84, v216, 0
	v_max_f32_e32 v218, 0, v218
	v_fmac_f32_e32 v216, v85, v217
	v_max_f32_e32 v219, 0, v219
	v_fmac_f32_e32 v216, v86, v218
	v_max_f32_e32 v220, 0, v220
	v_fmac_f32_e32 v216, v87, v219
	v_max_f32_e32 v221, 0, v221
	v_fmac_f32_e32 v216, v80, v220
	v_max_f32_e32 v222, 0, v222
	v_fmac_f32_e32 v216, v81, v221
	v_max_f32_e32 v223, 0, v223
	v_fmac_f32_e32 v216, v82, v222
	v_max_f32_e32 v224, 0, v224
	v_fmac_f32_e32 v216, v83, v223
	v_max_f32_e32 v225, 0, v225
	v_fmac_f32_e32 v216, v76, v224
	v_max_f32_e32 v226, 0, v226
	v_fmac_f32_e32 v216, v77, v225
	v_max_f32_e32 v227, 0, v227
	v_fmac_f32_e32 v216, v78, v226
	v_max_f32_e32 v228, 0, v228
	v_fmac_f32_e32 v216, v79, v227
	v_max_f32_e32 v229, 0, v229
	v_fmac_f32_e32 v216, v72, v228
	v_max_f32_e32 v230, 0, v230
	v_fmac_f32_e32 v216, v73, v229
	v_max_f32_e32 v231, 0, v231
	v_fmac_f32_e32 v216, v74, v230
	v_fmac_f32_e32 v216, v75, v231
	ds_write_b32 v207, v216
	s_branch .LBB0_160
.Lidx_exit_e:
	s_mov_b64 s[24:25], 0x8000
	s_cmp_gt_u32 s22, 3
	s_cbranch_scc1 .Lidx_x_e
	s_barrier
.Lidx_x_e:
	s_nop 3
	v_max_f32_e32 v0, 0, v0
	v_max_f32_e32 v1, 0, v1
	v_fma_f32 v0, v84, v0, 0
	v_max_f32_e32 v2, 0, v2
	v_fmac_f32_e32 v0, v85, v1
	v_max_f32_e32 v3, 0, v3
	v_fmac_f32_e32 v0, v86, v2
	v_max_f32_e32 v4, 0, v4
	v_fmac_f32_e32 v0, v87, v3
	v_max_f32_e32 v5, 0, v5
	v_fmac_f32_e32 v0, v80, v4
	v_max_f32_e32 v6, 0, v6
	v_fmac_f32_e32 v0, v81, v5
	v_max_f32_e32 v7, 0, v7
	v_fmac_f32_e32 v0, v82, v6
	v_max_f32_e32 v8, 0, v8
	v_fmac_f32_e32 v0, v83, v7
	v_max_f32_e32 v9, 0, v9
	v_fmac_f32_e32 v0, v76, v8
	v_max_f32_e32 v10, 0, v10
	v_fmac_f32_e32 v0, v77, v9
	v_max_f32_e32 v11, 0, v11
	v_fmac_f32_e32 v0, v78, v10
	v_max_f32_e32 v12, 0, v12
	v_fmac_f32_e32 v0, v79, v11
	v_max_f32_e32 v13, 0, v13
	v_fmac_f32_e32 v0, v72, v12
	v_max_f32_e32 v14, 0, v14
	v_fmac_f32_e32 v0, v73, v13
	v_max_f32_e32 v15, 0, v15
	v_fmac_f32_e32 v0, v74, v14
	v_fmac_f32_e32 v0, v75, v15
	ds_write_b32 v207, v0
